# slack work before the GEMM units, w_out copy split three ways (type A one item per wave, type-B workgroups without a gemv item two per wave)
# speedup vs baseline: 1.0305x; 1.0016x over previous
.LBB0_486:
	v_mov_b32_e32 v1, s6
	v_add_co_u32_e32 v2, vcc, 0x2940000, v1
	v_mov_b32_e32 v1, s7
	s_nop 0
	v_addc_co_u32_e32 v3, vcc, 0, v1, vcc
	flat_load_dwordx4 v[2:5], v[2:3]
	s_and_b32 s4, s21, -4
	s_or_b32 s11, s4, s22
	s_lshl_b32 s4, s11, 3
	s_add_i32 s10, s4, s28
	s_cmpk_gt_i32 s10, 0x7ff
	s_mov_b32 s4, 0x2940000
	s_mov_b32 s49, -1
	s_movk_i32 s50, 0x400
	s_mov_b32 s51, 0x8000
	s_bitcmp0_b32 s20, 2
	s_cbranch_scc1 .Ltr_go
	s_cmp_lt_i32 s11, 64
	s_cbranch_scc1 .LBB0_489
	s_addk_i32 s10, 0x200
	s_movk_i32 s49, 0x5ff
	s_movk_i32 s50, 0x200
	s_movk_i32 s51, 0x4000
.Ltr_go:
	s_cmpk_gt_i32 s10, 0x7ff
	s_cbranch_scc1 .LBB0_489
	v_mov_b32_e32 v1, s6
	v_add_co_u32_e32 v6, vcc, s4, v1
	v_mov_b32_e32 v1, s7
	s_nop 0
	v_addc_co_u32_e32 v7, vcc, 0, v1, vcc
	flat_load_dwordx2 v[8:9], v[6:7] offset:16
	s_lshl_b32 s8, s28, 14
	v_and_b32_e32 v1, 7, v0
	v_lshrrev_b32_e32 v10, 3, v178
	s_add_i32 s8, s8, 0
	v_lshlrev_b32_e32 v26, 4, v1
	v_mov_b32_e32 v27, 0
	v_mul_u32_u24_e32 v12, 0x84, v10
	v_mul_u32_u24_e32 v1, 0x420, v1
	v_lshlrev_b32_e32 v6, 2, v10
	v_add_u32_e32 v13, s8, v26
	s_mov_b64 s[4:5], 0x1e00000
	v_add3_u32 v11, s8, v1, v6
	v_lshl_add_u64 v[6:7], s[6:7], 0, v[26:27]
	v_add_u32_e32 v12, v13, v12
	s_lshl_b32 s12, s10, 5
	v_lshl_add_u64 v[6:7], v[6:7], 0, s[4:5]
	v_add_u32_e32 v13, 0x420, v12
	v_add_u32_e32 v14, 0x428, v12
	v_add_u32_e32 v15, 0x840, v12
	v_add_u32_e32 v16, 0x848, v12
	v_add_u32_e32 v17, 0xc60, v12
	v_add_u32_e32 v18, 0xc68, v12
	v_add_u32_e32 v19, 0x1080, v12
	v_add_u32_e32 v20, 0x1088, v12
	v_add_u32_e32 v21, 0x14a0, v12
	v_add_u32_e32 v22, 0x14a8, v12
	v_add_u32_e32 v23, 0x18c0, v12
	v_add_u32_e32 v24, 0x18c8, v12
	v_add_u32_e32 v25, 0x1ce0, v12
	s_waitcnt vmcnt(0) lgkmcnt(0)
	v_lshl_add_u64 v[8:9], v[8:9], 0, v[26:27]
	v_add_u32_e32 v26, 0x1ce8, v12
.LBB0_488:
	s_ashr_i32 s4, s10, 31
	s_lshr_b32 s4, s4, 26
	s_add_i32 s4, s10, s4
	s_lshl_b32 s5, s4, 5
	s_and_b32 s8, s4, 0xffffffc0
	s_and_b32 s4, s5, 0xfffff800
	v_or_b32_e32 v28, s8, v10
	s_sub_i32 s4, s12, s4
	v_ashrrev_i32_e32 v29, 31, v28
	v_or_b32_e32 v30, 8, v28
	v_or_b32_e32 v32, 16, v28
	v_or_b32_e32 v34, 24, v28
	v_or_b32_e32 v36, 32, v28
	v_or_b32_e32 v38, 40, v28
	v_or_b32_e32 v40, 48, v28
	v_or_b32_e32 v42, 56, v28
	s_ashr_i32 s5, s4, 31
	v_lshlrev_b64 v[28:29], 13, v[28:29]
	v_ashrrev_i32_e32 v31, 31, v30
	v_ashrrev_i32_e32 v33, 31, v32
	v_ashrrev_i32_e32 v35, 31, v34
	v_ashrrev_i32_e32 v37, 31, v36
	v_ashrrev_i32_e32 v39, 31, v38
	v_ashrrev_i32_e32 v41, 31, v40
	v_ashrrev_i32_e32 v43, 31, v42
	v_lshl_add_u64 v[44:45], s[4:5], 2, v[8:9]
	v_lshlrev_b64 v[30:31], 13, v[30:31]
	v_lshlrev_b64 v[32:33], 13, v[32:33]
	v_lshlrev_b64 v[34:35], 13, v[34:35]
	v_lshlrev_b64 v[36:37], 13, v[36:37]
	v_lshlrev_b64 v[38:39], 13, v[38:39]
	v_lshlrev_b64 v[40:41], 13, v[40:41]
	v_lshlrev_b64 v[42:43], 13, v[42:43]
	v_lshl_add_u64 v[60:61], v[44:45], 0, v[28:29]
	v_lshl_add_u64 v[62:63], v[44:45], 0, v[30:31]
	v_lshl_add_u64 v[64:65], v[44:45], 0, v[32:33]
	v_lshl_add_u64 v[66:67], v[44:45], 0, v[34:35]
	v_lshl_add_u64 v[68:69], v[44:45], 0, v[36:37]
	v_lshl_add_u64 v[70:71], v[44:45], 0, v[38:39]
	v_lshl_add_u64 v[72:73], v[44:45], 0, v[40:41]
	v_lshl_add_u64 v[74:75], v[44:45], 0, v[42:43]
	global_load_dwordx4 v[28:31], v[60:61], off nt
	global_load_dwordx4 v[32:35], v[62:63], off nt
	global_load_dwordx4 v[36:39], v[64:65], off nt
	global_load_dwordx4 v[40:43], v[66:67], off nt
	global_load_dwordx4 v[44:47], v[68:69], off nt
	global_load_dwordx4 v[48:51], v[70:71], off nt
	global_load_dwordx4 v[52:55], v[72:73], off nt
	global_load_dwordx4 v[56:59], v[74:75], off nt
	v_add_u32_e32 v62, s4, v10
	s_ashr_i32 s9, s8, 31
	v_ashrrev_i32_e32 v63, 31, v62
	v_lshl_add_u64 v[60:61], s[8:9], 1, v[6:7]
	v_lshlrev_b64 v[68:69], 12, v[62:63]
	v_lshl_add_u64 v[68:69], v[60:61], 0, v[68:69]
	v_add_u32_e32 v64, 8, v62
	v_ashrrev_i32_e32 v65, 31, v64
	v_lshlrev_b64 v[64:65], 12, v[64:65]
	v_lshl_add_u64 v[64:65], v[60:61], 0, v[64:65]
	v_add_u32_e32 v66, 16, v62
	v_ashrrev_i32_e32 v67, 31, v66
	v_lshlrev_b64 v[66:67], 12, v[66:67]
	s_add_i32 s4, s10, s50
	s_add_i32 s12, s12, s51
	s_cmp_gt_i32 s10, s49
	s_mov_b32 s10, s4
	s_waitcnt vmcnt(0)
	ds_write2_b32 v12, v28, v29 offset1:1
	ds_write2_b32 v12, v30, v31 offset0:2 offset1:3
	s_waitcnt vmcnt(6)
	ds_write2_b32 v13, v32, v33 offset1:1
	ds_write2_b32 v14, v34, v35 offset1:1
	s_waitcnt vmcnt(5)
	ds_write2_b32 v15, v36, v37 offset1:1
	ds_write2_b32 v16, v38, v39 offset1:1
	s_waitcnt vmcnt(4)
	ds_write2_b32 v17, v40, v41 offset1:1
	ds_write2_b32 v18, v42, v43 offset1:1
	s_waitcnt vmcnt(3)
	ds_write2_b32 v19, v44, v45 offset1:1
	ds_write2_b32 v20, v46, v47 offset1:1
	s_waitcnt vmcnt(2)
	ds_write2_b32 v21, v48, v49 offset1:1
	ds_write2_b32 v22, v50, v51 offset1:1
	s_waitcnt vmcnt(1)
	ds_write2_b32 v23, v52, v53 offset1:1
	ds_write2_b32 v24, v54, v55 offset1:1
	s_waitcnt vmcnt(0)
	ds_write2_b32 v25, v56, v57 offset1:1
	ds_write2_b32 v26, v58, v59 offset1:1
	s_waitcnt lgkmcnt(0)
	ds_read2_b32 v[28:29], v11 offset1:33
	s_waitcnt lgkmcnt(0)
	v_cvt_pk_bf16_f32 v28, v28, v29
	ds_read2_b32 v[30:31], v11 offset0:66 offset1:99
	s_waitcnt lgkmcnt(0)
	v_cvt_pk_bf16_f32 v29, v30, v31
	ds_read2_b32 v[30:31], v11 offset0:132 offset1:165
	s_waitcnt lgkmcnt(0)
	v_cvt_pk_bf16_f32 v30, v30, v31
	ds_read2_b32 v[32:33], v11 offset0:198 offset1:231
	s_waitcnt lgkmcnt(0)
	v_cvt_pk_bf16_f32 v31, v32, v33
	flat_store_dwordx4 v[68:69], v[28:31]
	ds_read2_b32 v[28:29], v11 offset0:8 offset1:41
	v_lshl_add_u64 v[34:35], v[60:61], 0, v[66:67]
	s_waitcnt lgkmcnt(0)
	v_cvt_pk_bf16_f32 v28, v28, v29
	ds_read2_b32 v[30:31], v11 offset0:74 offset1:107
	s_waitcnt lgkmcnt(0)
	v_cvt_pk_bf16_f32 v29, v30, v31
	ds_read2_b32 v[30:31], v11 offset0:140 offset1:173
	s_waitcnt lgkmcnt(0)
	v_cvt_pk_bf16_f32 v30, v30, v31
	ds_read2_b32 v[32:33], v11 offset0:206 offset1:239
	s_waitcnt lgkmcnt(0)
	v_cvt_pk_bf16_f32 v31, v32, v33
	flat_store_dwordx4 v[64:65], v[28:31]
	ds_read2_b32 v[28:29], v11 offset0:16 offset1:49
	s_waitcnt lgkmcnt(0)
	v_cvt_pk_bf16_f32 v28, v28, v29
	ds_read2_b32 v[30:31], v11 offset0:82 offset1:115
	s_waitcnt lgkmcnt(0)
	v_cvt_pk_bf16_f32 v29, v30, v31
	ds_read2_b32 v[30:31], v11 offset0:148 offset1:181
	s_waitcnt lgkmcnt(0)
	v_cvt_pk_bf16_f32 v30, v30, v31
	ds_read2_b32 v[32:33], v11 offset0:214 offset1:247
	s_waitcnt lgkmcnt(0)
	v_cvt_pk_bf16_f32 v31, v32, v33
	flat_store_dwordx4 v[34:35], v[28:31]
	v_add_u32_e32 v34, 24, v62
	ds_read2_b32 v[28:29], v11 offset0:24 offset1:57
	v_ashrrev_i32_e32 v35, 31, v34
	s_waitcnt lgkmcnt(0)
	v_cvt_pk_bf16_f32 v28, v28, v29
	ds_read2_b32 v[30:31], v11 offset0:90 offset1:123
	v_lshlrev_b64 v[34:35], 12, v[34:35]
	s_waitcnt lgkmcnt(0)
	v_cvt_pk_bf16_f32 v29, v30, v31
	ds_read2_b32 v[30:31], v11 offset0:156 offset1:189
	v_lshl_add_u64 v[34:35], v[60:61], 0, v[34:35]
	s_waitcnt lgkmcnt(0)
	v_cvt_pk_bf16_f32 v30, v30, v31
	ds_read2_b32 v[32:33], v11 offset0:222 offset1:255
	s_waitcnt lgkmcnt(0)
	v_cvt_pk_bf16_f32 v31, v32, v33
	flat_store_dwordx4 v[34:35], v[28:31]
	s_waitcnt lgkmcnt(0)
	s_cbranch_scc0 .LBB0_488
